# GEMM2+3 phase: GEMM3 panel wait deferred past the previous tile's epilogue (uniform poll at the last K-iteration; if the panel is not ready the iteration re-stages own tiles, then epilogue, spin, one
# speedup vs baseline: 1.0212x; 1.0119x over previous
.LBB0_861:
	s_mov_b32 s100, 0
	v_writelane_b32 v255, s100, 2
	v_bfe_i32 v4, v1, 27, 1
	v_lshlrev_b32_e32 v2, 4, v1
	v_lshrrev_b32_e32 v4, 22, v4
	v_add_u32_e32 v4, v2, v4
	v_and_b32_e32 v4, 0xfffffc00, v4
	v_sub_u32_e32 v4, v2, v4
	s_lshl_b32 s0, s97, 23
	v_readlane_b32 s2, v253, 28
	v_ashrrev_i32_e32 v3, 31, v1
	v_lshrrev_b32_e32 v5, 4, v4
	v_readlane_b32 s3, v253, 29
	s_add_u32 s16, s2, s0
	v_lshrrev_b32_e32 v3, 26, v3
	v_bitop3_b32 v4, v5, v4, 32 bitop3:0x6c
	s_addc_u32 s17, s3, 0
	v_readlane_b32 s2, v253, 26
	v_add_u32_e32 v3, v1, v3
	v_ashrrev_i32_e32 v6, 31, v4
	v_readlane_b32 s3, v253, 27
	s_add_u32 s19, s2, s0
	v_readlane_b32 s0, v254, 31
	v_ashrrev_i32_e32 v3, 6, v3
	v_lshrrev_b32_e32 v6, 26, v6
	s_addc_u32 s22, s3, 0
	v_readlane_b32 s1, v254, 32
	v_lshlrev_b32_e32 v5, 3, v3
	v_add_u32_e32 v6, v4, v6
	s_and_b64 s[0:1], s[0:1], exec
	v_and_b32_e32 v5, -16, v5
	v_ashrrev_i32_e32 v7, 6, v6
	v_and_b32_e32 v6, 0xc0, v6
	s_cselect_b32 s0, s19, s16
	v_readlane_b32 s2, v254, 38
	v_add_u32_e32 v5, v7, v5
	v_sub_u32_e32 v4, v4, v6
	s_cselect_b32 s1, s22, s17
	s_add_u32 s0, s0, s2
	v_lshlrev_b32_e32 v3, 5, v3
	v_ashrrev_i16_sdwa v4, v223, sext(v4) dst_sel:DWORD dst_unused:UNUSED_PAD src0_sel:DWORD src1_sel:BYTE_0
	v_lshlrev_b32_e32 v6, 1, v5
	v_lshrrev_b32_e32 v8, 2, v5
	v_and_b32_e32 v7, 3, v7
	s_mov_b32 s2, 0xfffe0
	v_and_b32_e32 v3, 32, v3
	v_bfe_i32 v4, v4, 0, 16
	v_and_b32_e32 v6, 24, v6
	v_and_b32_e32 v8, 4, v8
	v_and_or_b32 v7, v5, s2, v7
	v_or3_b32 v6, v7, v8, v6
	v_add_lshl_u32 v3, v3, v4, 1
	v_add_u32_e32 v2, 0x2000, v2
	v_lshl_add_u32 v204, v5, 12, v3
	v_lshl_add_u32 v206, v6, 12, v3
	v_ashrrev_i32_e32 v3, 31, v2
	v_lshrrev_b32_e32 v3, 22, v3
	v_add_u32_e32 v3, v2, v3
	v_ashrrev_i32_e32 v3, 10, v3
	v_mul_i32_i24_e32 v4, 0x400, v3
	v_sub_u32_e32 v2, v2, v4
	v_lshrrev_b32_e32 v4, 4, v2
	v_bitop3_b32 v2, v4, v2, 32 bitop3:0x6c
	v_ashrrev_i32_e32 v5, 31, v2
	v_lshrrev_b32_e32 v5, 26, v5
	v_lshlrev_b32_e32 v4, 3, v3
	v_add_u32_e32 v5, v2, v5
	s_addc_u32 s1, s1, 0
	v_and_b32_e32 v4, -16, v4
	v_ashrrev_i32_e32 v6, 6, v5
	s_add_u32 s10, s0, 0x80000
	v_add_u32_e32 v4, v6, v4
	v_and_b32_e32 v5, 0xc0, v5
	v_and_b32_e32 v6, 3, v6
	s_addc_u32 s11, s1, 0
	v_sub_u32_e32 v2, v2, v5
	v_and_or_b32 v6, v4, s2, v6
	s_ashr_i32 s2, s4, 6
	v_lshlrev_b32_e32 v3, 5, v3
	v_ashrrev_i16_sdwa v2, v223, sext(v2) dst_sel:DWORD dst_unused:UNUSED_PAD src0_sel:DWORD src1_sel:BYTE_0
	v_lshlrev_b32_e32 v5, 1, v4
	v_lshrrev_b32_e32 v7, 2, v4
	s_lshl_b32 s23, s2, 10
	v_and_b32_e32 v3, 32, v3
	v_bfe_i32 v2, v2, 0, 16
	v_and_b32_e32 v5, 24, v5
	v_and_b32_e32 v7, 4, v7
	s_add_i32 s24, s23, 0
	v_or3_b32 v5, v6, v7, v5
	v_add_lshl_u32 v2, v3, v2, 1
	s_add_i32 m0, s24, 0x10000
	v_lshl_add_u32 v210, v5, 12, v2
	global_load_lds_dwordx4 v206, s[0:1]
	s_add_i32 m0, s24, 0x12000
	s_add_i32 s25, s24, 0x2000
	global_load_lds_dwordx4 v210, s[0:1]
	s_add_i32 m0, s24, 0x14000
	v_lshl_add_u32 v208, v4, 12, v2
	global_load_lds_dwordx4 v206, s[10:11]
	s_add_i32 m0, s24, 0x16000
	s_add_i32 s36, s24, 0x4000
	global_load_lds_dwordx4 v210, s[10:11]
	v_readlane_b32 s10, v254, 39
	s_mov_b32 m0, s24
	v_readlane_b32 s11, v254, 40
	s_add_i32 s37, s24, 0x6000
	s_ashr_i32 s3, s4, 8
	v_mov_b32_e32 v207, v0
	v_mov_b32_e32 v211, v0
	s_cmp_eq_u32 s3, 1
	global_load_lds_dwordx4 v204, s[10:11]
	s_mov_b32 m0, s25
	v_lshl_add_u64 v[2:3], s[0:1], 0, v[206:207]
	global_load_lds_dwordx4 v208, s[10:11]
	v_readlane_b32 s10, v254, 41
	s_mov_b32 m0, s36
	v_readlane_b32 s11, v254, 42
	v_lshl_add_u64 v[4:5], s[0:1], 0, v[210:211]
	s_nop 3
	global_load_lds_dwordx4 v204, s[10:11]
	s_mov_b32 m0, s37
	s_nop 0
	global_load_lds_dwordx4 v208, s[10:11]
	s_cselect_b64 s[10:11], -1, 0
	s_cmp_lg_u32 s3, 1
	s_cbranch_scc1 .LBB0_863
	s_barrier

.LBB0_869:
	s_cmp_lg_u32 s97, 30
	s_cselect_b64 s[2:3], -1, 0
	s_or_b64 s[4:5], s[48:49], s[2:3]
	s_or_b64 s[4:5], s[4:5], s[50:51]
	s_and_b64 vcc, exec, s[4:5]
	s_cbranch_vccnz .LBB0_879
	v_readlane_b32 s100, v255, 2
	s_nop 0
	s_cmp_eq_u32 s100, 2
	s_cbranch_scc1 .Ldef_spin
	s_barrier
	v_readfirstlane_b32 s100, v220
	s_nop 0
	s_cmp_eq_u32 s100, 0
	s_cbranch_scc0 .Ldef_nopoll
	global_load_dword v1, v0, s[54:55] sc1
	v_mov_b32_e32 v2, 0x23fc0
	s_waitcnt vmcnt(0)
	ds_write_b32 v2, v1
	s_waitcnt lgkmcnt(0)
.Ldef_nopoll:
	s_barrier
	v_mov_b32_e32 v2, 0x23fc0
	ds_read_b32 v1, v2
	s_waitcnt lgkmcnt(0)
	v_readfirstlane_b32 s100, v1
	s_nop 0
	s_cmp_gt_u32 s100, 63
	s_cbranch_scc1 .Ldef_spin
	s_mov_b32 s100, 1
	v_writelane_b32 v255, s100, 2
	s_mov_b32 s92, s44
	s_mov_b32 s85, s45
	s_mov_b32 s96, s46
	s_mov_b32 s93, s47
	s_branch .LBB0_879
.Ldef_spin:
	s_mov_b32 s34, 0x400001
	s_branch .LBB0_872

.LBB0_881:
	v_readlane_b32 s100, v255, 2
	s_nop 0
	s_cmp_eq_u32 s100, 2
	s_cbranch_scc0 .Ldef_norm
	s_mov_b32 s100, 0
	v_writelane_b32 v255, s100, 2
	s_branch .LBB0_864

.Ldef_chk:
	v_readlane_b32 s100, v255, 2
	s_nop 0
	s_cmp_eq_u32 s100, 1
	s_cbranch_scc0 .LBB0_864
	s_mov_b32 s92, s38
	s_mov_b32 s85, s39
	s_mov_b32 s96, s0
	s_mov_b32 s93, s1
	s_mov_b32 s100, 2
	v_writelane_b32 v255, s100, 2
	s_mov_b32 s97, 30
	s_branch .LBB0_867

	.amdhsa_kernel _Z8mega_fwd6Params
		.amdhsa_group_segment_fixed_size 0
		.amdhsa_private_segment_fixed_size 0
		.amdhsa_kernarg_size 464
		.amdhsa_user_sgpr_count 2
		.amdhsa_user_sgpr_dispatch_ptr 0
		.amdhsa_user_sgpr_queue_ptr 0
		.amdhsa_user_sgpr_kernarg_segment_ptr 1
		.amdhsa_user_sgpr_dispatch_id 0
		.amdhsa_user_sgpr_kernarg_preload_length 0
		.amdhsa_user_sgpr_kernarg_preload_offset 0
		.amdhsa_user_sgpr_private_segment_size 0
		.amdhsa_uses_dynamic_stack 0
		.amdhsa_enable_private_segment 0
		.amdhsa_system_sgpr_workgroup_id_x 1
		.amdhsa_system_sgpr_workgroup_id_y 0
		.amdhsa_system_sgpr_workgroup_id_z 0
		.amdhsa_system_sgpr_workgroup_info 0
		.amdhsa_system_vgpr_workitem_id 2
		.amdhsa_next_free_vgpr 256
		.amdhsa_next_free_sgpr 102
		.amdhsa_accum_offset 256
		.amdhsa_reserve_vcc 1
		.amdhsa_float_round_mode_32 0
		.amdhsa_float_round_mode_16_64 0
		.amdhsa_float_denorm_mode_32 3
		.amdhsa_float_denorm_mode_16_64 3
		.amdhsa_dx10_clamp 1
		.amdhsa_ieee_mode 1
		.amdhsa_fp16_overflow 0
		.amdhsa_tg_split 0
		.amdhsa_exception_fp_ieee_invalid_op 0
		.amdhsa_exception_fp_denorm_src 0
		.amdhsa_exception_fp_ieee_div_zero 0
		.amdhsa_exception_fp_ieee_overflow 0
		.amdhsa_exception_fp_ieee_underflow 0
		.amdhsa_exception_fp_ieee_inexact 0
		.amdhsa_exception_int_div_zero 0
	.end_amdhsa_kernel

amdhsa.kernels:
  - .agpr_count:     0
    .args:
      - .offset:         0
        .size:           208
        .value_kind:     by_value
      - .offset:         208
        .size:           4
        .value_kind:     hidden_block_count_x
      - .offset:         212
        .size:           4
        .value_kind:     hidden_block_count_y
      - .offset:         216
        .size:           4
        .value_kind:     hidden_block_count_z
      - .offset:         220
        .size:           2
        .value_kind:     hidden_group_size_x
      - .offset:         222
        .size:           2
        .value_kind:     hidden_group_size_y
      - .offset:         224
        .size:           2
        .value_kind:     hidden_group_size_z
      - .offset:         226
        .size:           2
        .value_kind:     hidden_remainder_x
      - .offset:         228
        .size:           2
        .value_kind:     hidden_remainder_y
      - .offset:         230
        .size:           2
        .value_kind:     hidden_remainder_z
      - .offset:         248
        .size:           8
        .value_kind:     hidden_global_offset_x
      - .offset:         256
        .size:           8
        .value_kind:     hidden_global_offset_y
      - .offset:         264
        .size:           8
        .value_kind:     hidden_global_offset_z
      - .offset:         272
        .size:           2
        .value_kind:     hidden_grid_dims
      - .offset:         296
        .size:           8
        .value_kind:     hidden_multigrid_sync_arg
      - .offset:         328
        .size:           4
        .value_kind:     hidden_dynamic_lds_size
    .group_segment_fixed_size: 0
    .kernarg_segment_align: 8
    .kernarg_segment_size: 464
    .language:       OpenCL C
    .language_version:
      - 2
      - 0
    .max_flat_workgroup_size: 512
    .name:           _Z8mega_fwd6Params
    .private_segment_fixed_size: 0
    .sgpr_count:     108
    .sgpr_spill_count: 160
    .symbol:         _Z8mega_fwd6Params.kd
    .uniform_work_group_size: 1
    .uses_dynamic_stack: false
    .vgpr_count:     256
    .vgpr_spill_count: 0
    .wavefront_size: 64
